# g11: g8 + acquire-invalidate hoisting - buffer_inv sc1 issued right after the arrive atomic so it overlaps the flag poll (3 PANEL_SYNC sites)
# baseline (speedup 1.0000x reference)
; __device__ __forceinline__ void panel_barrier(unsigned* cnt, unsigned target, bool full) {
;     ...
;         __builtin_amdgcn_fence(__ATOMIC_ACQUIRE, "agent");
;         asm volatile("s_waitcnt vmcnt(0)" ::: "memory");
.LBB0_121:
	s_nop 0
	s_waitcnt vmcnt(0)

; __device__ __forceinline__ void panel_barrier(unsigned* cnt, unsigned target, bool full) {
;     ...
;     if (threadIdx.x == 0) {
;         if (full) { __builtin_amdgcn_fence(__ATOMIC_RELEASE, "agent"); asm volatile("s_waitcnt vmcnt(0)" ::: "memory"); }
;         (void)__hip_atomic_fetch_add(cnt, 1u, __ATOMIC_RELAXED, __HIP_MEMORY_SCOPE_AGENT);
;         unsigned sp = 0;
;         while (__hip_atomic_load(cnt, __ATOMIC_RELAXED, __HIP_MEMORY_SCOPE_AGENT) < target) { __builtin_amdgcn_s_sleep(1); if (++sp > (1u << 22)) break; }
;         __builtin_amdgcn_fence(__ATOMIC_ACQUIRE, "agent");
.LBB0_344:
	s_or_b64 exec, exec, s[28:29]
	buffer_inv sc1
	s_add_i32 s9, s37, 4
	s_mov_b32 s24, 0x400001
	s_branch .LBB0_346

; __device__ __forceinline__ void panel_barrier(unsigned* cnt, unsigned target, bool full) {
;     ...
;     if (threadIdx.x == 0) {
;         if (full) { __builtin_amdgcn_fence(__ATOMIC_RELEASE, "agent"); asm volatile("s_waitcnt vmcnt(0)" ::: "memory"); }
;         (void)__hip_atomic_fetch_add(cnt, 1u, __ATOMIC_RELAXED, __HIP_MEMORY_SCOPE_AGENT);
;         unsigned sp = 0;
;         while (__hip_atomic_load(cnt, __ATOMIC_RELAXED, __HIP_MEMORY_SCOPE_AGENT) < target) { __builtin_amdgcn_s_sleep(1); if (++sp > (1u << 22)) break; }
;         __builtin_amdgcn_fence(__ATOMIC_ACQUIRE, "agent");
.LBB0_380:
	s_or_b64 exec, exec, s[28:29]
	buffer_inv sc1
	s_add_i32 s9, s37, 8
	s_mov_b32 s24, 0x400001
	s_branch .LBB0_382

; __device__ __forceinline__ void panel_barrier(unsigned* cnt, unsigned target, bool full) {
;     ...
;     if (threadIdx.x == 0) {
;         if (full) { __builtin_amdgcn_fence(__ATOMIC_RELEASE, "agent"); asm volatile("s_waitcnt vmcnt(0)" ::: "memory"); }
;         (void)__hip_atomic_fetch_add(cnt, 1u, __ATOMIC_RELAXED, __HIP_MEMORY_SCOPE_AGENT);
;         unsigned sp = 0;
;         while (__hip_atomic_load(cnt, __ATOMIC_RELAXED, __HIP_MEMORY_SCOPE_AGENT) < target) { __builtin_amdgcn_s_sleep(1); if (++sp > (1u << 22)) break; }
;         __builtin_amdgcn_fence(__ATOMIC_ACQUIRE, "agent");
.LBB0_434:
	s_or_b64 exec, exec, s[28:29]
	buffer_inv sc1
	s_mov_b32 s9, 0x400001
	s_branch .LBB0_436
